# grid barrier: XCD leader bumps per-XCD generation before its own L1/L2 invalidate (off critical path); P4 DSA deeper prefetch + running addresses
# speedup vs baseline: 1.0057x; 1.0057x over previous
; __device__ __forceinline__ unsigned xb_ld(unsigned* p)              { return __hip_atomic_load(p, __ATOMIC_RELAXED, __HIP_MEMORY_SCOPE_AGENT); }
; __device__ __forceinline__ unsigned xb_add(unsigned* p, unsigned v) { return __hip_atomic_fetch_add(p, v, __ATOMIC_RELAXED, __HIP_MEMORY_SCOPE_AGENT); }
; #define XB_SPIN(cond, bar) do { unsigned _sp = 0; while (cond) { __builtin_amdgcn_s_sleep(1); \
;     if ((++_sp & 255u) == 0u) { if (xb_ld(&(bar)[XB_TMO])) break; if (_sp > XB_SPIN_CAP) { atomicAdd(&(bar)[XB_TMO], 1u); break; } } } } while (0)
; __device__ __forceinline__ void xcd_barrier(const XcdBarrier& b) {
;     ...
;             __builtin_amdgcn_fence(__ATOMIC_RELEASE, "agent");
;             asm volatile("s_waitcnt vmcnt(0)" ::: "memory");
;             const unsigned og = xb_add(&bar[XB_TOP], 1u);
;             const unsigned tg = og / nx;
;             if (og + 1u == (tg + 1u) * nx) xb_add(&bar[XB_TOPGEN], 1u);
;             else XB_SPIN(xb_ld(&bar[XB_TOPGEN]) == tg, bar);
;             __builtin_amdgcn_fence(__ATOMIC_ACQUIRE, "agent");
;             xb_add(&bar[XB_XGEN(b.x)], 1u);
;             asm volatile("s_waitcnt vmcnt(0)" ::: "memory");
.LBB0_234:
	s_or_b64 exec, exec, s[6:7]
	v_mov_b32_e32 v1, 0x2000
	v_mov_b32_e32 v2, 1
	s_waitcnt vmcnt(0)
	global_atomic_add v1, v2, s[4:5] offset:1024
	buffer_inv sc1
	s_waitcnt vmcnt(0)

; #define LAS __attribute__((address_space(3)))
; #define SB_LD(KF, VR, KK) do { _Pragma("unroll") for (int i = 0; i < 4; ++i) { const int id = lane + 64 * i; KF[i] = *(const bf16x8*)(kcol + (size_t)((KK) + (id >> 3)) * QKVW + (id & 7) * 8); VR[i] = *(const u32x4*)(vcol + (size_t)((KK) + (id >> 3)) * QKVW + (id & 7) * 8); } } while (0)
; __device__ __forceinline__ void ld_q(bf16x8 (&qf)[4], const bf16_t* row0, size_t stride, LAS unsigned char* kl, int lane) {
;     bf16x8 raw[4];
; #pragma unroll
;     for (int i = 0; i < 4; ++i) { const int id = lane + 64 * i; raw[i] = *(const bf16x8*)(row0 + (size_t)(id >> 3) * stride + (id & 7) * 8); }
;     k_frag(qf, kl, raw, lane);
; }
; __device__ __forceinline__ void sb_item(bf16_t* qkv, LAS unsigned char* vl, int h, int qb, int lane, bool dry) {
;     LAS unsigned char* kl = vl + VL_BYTES;
;     const int r = lane & 31, hh = lane >> 5, t0 = qb * 32;
;     bf16_t* q0 = qkv + (size_t)t0 * QKVW + C_QA + h * 64;
;     bf16x8 qf[4]; ld_q(qf, q0, QKVW, kl, lane);
;     f32x16 o[2];
; #pragma unroll
;     for (int i = 0; i < 16; ++i) { o[0][i] = 0.f; o[1][i] = 0.f; }
;     float carry = 1.f;
;     const bf16_t* kcol = qkv + C_KA + h * 64; const bf16_t* vcol = qkv + C_VA + h * 64;
;     ...
;     bf16x8 kfA[4], kfB[4]; u32x4 vrA[4], vrB[4];
;     int k0 = t0;
;     SB_LD(kfA, vrA, k0);
.LBB0_756:
	s_mul_i32 s4, s4, s46
	s_add_i32 s66, s45, s4
	s_cmpk_gt_i32 s66, 0x1fff
	s_cbranch_scc1 .LBB0_753
	s_cmpk_gt_i32 s66, 0x7ff
	s_cbranch_scc0 .LBB0_769
	s_cmpk_gt_u32 s66, 0xfff
	s_waitcnt vmcnt(2)
	v_lshlrev_b32_e32 v136, 1, v150
	v_lshlrev_b32_e32 v134, 1, v152
	v_lshlrev_b32_e32 v132, 1, v154
	v_lshlrev_b32_e32 v130, 1, v156
	s_cbranch_scc0 .LBB0_771
	v_or_b32_e32 v200, 2, v177
	v_or_b32_e32 v201, 3, v147
	v_or_b32_e32 v202, 8, v177
	v_or_b32_e32 v203, 9, v177
	v_or_b32_e32 v204, 10, v177
	v_or_b32_e32 v205, 11, v147
	v_or_b32_e32 v206, 16, v177
	v_or_b32_e32 v207, 17, v177
	s_and_b32 s5, s66, 0x1ff
	s_add_i32 s4, s66, 0xfffff000
	s_lshl_b32 s6, s5, 18
	s_add_u32 s6, s43, s6
	s_addc_u32 s7, s44, 0
	s_lshr_b32 s4, s4, 2
	s_and_b32 s16, s4, 0x3fffff80
	s_add_u32 s38, s6, s16
	s_addc_u32 s39, s7, 0
	v_lshlrev_b32_e32 v148, 1, v146
	v_lshl_add_u64 v[2:3], s[38:39], 0, v[148:149]
	v_mov_b32_e32 v137, v149
	v_lshl_add_u64 v[4:5], v[2:3], 0, v[136:137]
	v_mov_b32_e32 v135, v149
	v_mov_b32_e32 v133, v149
	v_mov_b32_e32 v131, v149
	v_lshl_add_u64 v[6:7], v[2:3], 0, v[134:135]
	global_load_dwordx4 v[10:13], v[4:5], off
	global_load_dwordx4 v[14:17], v[6:7], off
	v_lshl_add_u64 v[4:5], v[2:3], 0, v[132:133]
	v_lshl_add_u64 v[2:3], v[2:3], 0, v[130:131]
	s_lshl_b32 s67, s5, 5
	global_load_dwordx4 v[34:37], v[4:5], off
	global_load_dwordx4 v[38:41], v[2:3], off
	v_or_b32_e32 v2, s67, v147
	s_waitcnt vmcnt(5)
	v_lshl_add_u64 v[138:139], v[158:159], 0, s[16:17]
	v_lshlrev_b32_e32 v148, 13, v2
	v_lshl_add_u64 v[140:141], v[160:161], 0, s[16:17]
	v_lshl_add_u64 v[2:3], v[138:139], 0, v[148:149]
	v_lshl_add_u64 v[4:5], v[140:141], 0, v[148:149]
	global_load_dwordx4 v[50:53], v[2:3], off
	global_load_dwordx4 v[54:57], v[4:5], off
	v_or_b32_e32 v2, s67, v151
	v_lshlrev_b32_e32 v148, 13, v2
	v_lshl_add_u64 v[2:3], v[138:139], 0, v[148:149]
	v_lshl_add_u64 v[4:5], v[140:141], 0, v[148:149]
	global_load_dwordx4 v[58:61], v[2:3], off
	global_load_dwordx4 v[62:65], v[4:5], off
	v_or_b32_e32 v2, s67, v153
	v_lshlrev_b32_e32 v148, 13, v2
	v_lshl_add_u64 v[2:3], v[138:139], 0, v[148:149]
	v_lshl_add_u64 v[4:5], v[140:141], 0, v[148:149]
	global_load_dwordx4 v[66:69], v[2:3], off
	global_load_dwordx4 v[70:73], v[4:5], off
	v_or_b32_e32 v2, s67, v155
	v_lshlrev_b32_e32 v148, 13, v2
	v_lshl_add_u64 v[2:3], v[138:139], 0, v[148:149]
	v_lshl_add_u64 v[4:5], v[140:141], 0, v[148:149]
	global_load_dwordx4 v[86:89], v[2:3], off
	global_load_dwordx4 v[94:97], v[4:5], off
	v_add_u32_e32 v131, v157, v167
	v_add_u32_e32 v133, v173, v175
	v_and_b32_e32 v2, 64, v217
	v_xor_b32_e32 v9, 32, v217
	v_add_u32_e32 v42, 64, v2
	v_cmp_lt_i32_e32 vcc, v9, v42
	v_mov_b32_e32 v18, 0
	v_mov_b32_e32 v137, 1.0
	v_cndmask_b32_e32 v9, v217, v9, vcc
	v_mov_b32_e32 v19, v18
	v_mov_b32_e32 v20, v18
	v_mov_b32_e32 v21, v18
	v_mov_b32_e32 v22, v18
	v_mov_b32_e32 v23, v18
	v_mov_b32_e32 v24, v18
	v_mov_b32_e32 v25, v18
	v_mov_b32_e32 v26, v18
	v_mov_b32_e32 v27, v18
	v_mov_b32_e32 v28, v18
	v_mov_b32_e32 v29, v18
	v_mov_b32_e32 v30, v18
	v_mov_b32_e32 v31, v18
	v_mov_b32_e32 v32, v18
	v_mov_b32_e32 v33, v18
	v_mov_b32_e32 v2, v18
	v_mov_b32_e32 v3, v18
	v_mov_b32_e32 v4, v18
	v_mov_b32_e32 v5, v18
	v_mov_b32_e32 v6, v18
	v_mov_b32_e32 v7, v18
	v_mov_b32_e32 v8, v18
	v_lshlrev_b32_e32 v135, 2, v9
	s_mov_b32 s16, s67
	v_mov_b32_e32 v9, v18
	s_waitcnt vmcnt(11)
	ds_write_b128 v131, v[10:13] offset:4608
	s_waitcnt vmcnt(10)
	ds_write_b128 v131, v[14:17] offset:5760
	s_waitcnt vmcnt(9)
	ds_write_b128 v131, v[34:37] offset:6912
	s_waitcnt vmcnt(8)
	ds_write_b128 v131, v[38:41] offset:8064
	ds_read_b128 v[110:113], v133 offset:4608
	ds_read_b128 v[118:121], v133 offset:4640
	ds_read_b128 v[122:125], v133 offset:4672
	ds_read_b128 v[126:129], v133 offset:4704
	v_mov_b32_e32 v10, v18
	v_mov_b32_e32 v11, v18
	v_mov_b32_e32 v12, v18
	v_mov_b32_e32 v13, v18
	v_mov_b32_e32 v14, v18
	v_mov_b32_e32 v15, v18
	v_mov_b32_e32 v16, v18
	v_mov_b32_e32 v17, v18
	s_branch .LBB0_761

; #define DSA_LD(KF, VR, KK) do { _Pragma("unroll") for (int i = 0; i < 4; ++i) { const int id = lane + 64 * i; KF[i] = *(const bf16x8*)(kcol + (size_t)(cm + (((KK) + (id >> 3)) << sh)) * QKVW + (id & 7) * 8); VR[i] = *(const u32x4*)(vcol + (size_t)(cm + (((KK) + (id >> 3)) << sh)) * QKVW + (id & 7) * 8); } } while (0)
; __device__ __forceinline__ void dsa_item(bf16_t* qkv, const float* mref_tab, LAS unsigned char* vl, int hs, int c, int i0, int lane, bool dry) {
;     ...
;     for (int g = 0; g < 3; ++g) {
;         const int sh = 2 * g, rr_ = 1 << sh, head = 4 * g + hs, cm = c & (rr_ - 1), cd = c >> sh, st = 16 >> sh;
;         bf16x8 qf[4]; ld_q(qf, qkv + (size_t)(c + 16 * i0) * QKVW + C_QB + head * 64, (size_t)16 * QKVW, kl, lane);
;         const bf16_t* kcol = qkv + C_KB + head * 64; const bf16_t* vcol = qkv + C_VB + head * 64;
;         const int qi = cd + st * (i0 + r);
;         const int qmin = cd + st * i0, qmax = cd + st * (i0 + 31);
;         int ks = qmin - 128; ks = ks < 0 ? 0 : ks; ks &= ~31;
;     ...
;         bf16x8 kfA[4], kfB[4]; u32x4 vrA[4], vrB[4];
;         int k0 = ks;
;         DSA_LD(kfA, vrA, k0);
;         for (;;) {
;             const bool m1 = k0 + 32 <= qmax; if (m1) DSA_LD(kfB, vrB, k0 + 32);
;             DSA_TILE(kfA, vrA, k0);
.LBB0_784:
	s_lshl_b32 s63, s16, 1
	s_lshl_b32 s70, 0x40000, s63
	s_mov_b32 s71, 0
	s_lshl_b32 s38, -1, s63
	s_andn2_b32 s64, s41, s38
	s_lshl_b32 s38, s16, 8
	s_lshr_b32 s67, 16, s63
	s_add_i32 s38, s38, s40
	s_ashr_i32 s66, s41, s63
	s_ashr_i32 s39, s38, 31
	s_mul_i32 s65, s67, s62
	s_lshl_b64 s[38:39], s[38:39], 1
	s_add_i32 s68, s65, s66
	v_lshl_add_u64 v[58:59], v[190:191], 0, s[38:39]
	s_max_i32 s65, s68, 0x80
	v_add_co_u32_e32 v54, vcc, s54, v58
	s_and_b32 s65, s65, 0x7ffffe0
	s_nop 0
	v_addc_co_u32_e32 v55, vcc, 0, v59, vcc
	s_addk_i32 s65, 0xff80
	v_add_co_u32_e32 v60, vcc, s55, v58
	s_waitcnt vmcnt(7)
	v_or_b32_e32 v98, s65, v147
	v_addc_co_u32_e32 v61, vcc, 0, v59, vcc
	v_lshlrev_b32_e32 v98, s63, v98
	s_waitcnt vmcnt(5)
	v_or_b32_e32 v106, s65, v151
	v_add_co_u32_e32 v62, vcc, s56, v58
	v_add_u32_e32 v148, s64, v98
	v_lshlrev_b32_e32 v106, s63, v106
	v_or_b32_e32 v114, s65, v153
	v_addc_co_u32_e32 v63, vcc, 0, v59, vcc
	v_lshlrev_b64 v[98:99], 13, v[148:149]
	v_add_u32_e32 v148, s64, v106
	v_lshlrev_b32_e32 v114, s63, v114
	global_load_dwordx4 v[50:53], v[58:59], off offset:3072
	s_nop 0
	global_load_dwordx4 v[54:57], v[54:55], off offset:3072
	s_nop 0
	global_load_dwordx4 v[58:61], v[60:61], off offset:3072
	s_nop 0
	global_load_dwordx4 v[62:65], v[62:63], off offset:3072
	v_lshlrev_b64 v[106:107], 13, v[148:149]
	v_add_u32_e32 v148, s64, v114
	v_lshl_add_u64 v[192:193], v[168:169], 0, s[38:39]
	v_lshl_add_u64 v[194:195], v[170:171], 0, s[38:39]
	v_lshlrev_b64 v[114:115], 13, v[148:149]
	v_lshl_add_u64 v[100:101], v[192:193], 0, v[98:99]
	v_lshl_add_u64 v[102:103], v[194:195], 0, v[98:99]
	v_lshl_add_u64 v[108:109], v[192:193], 0, v[106:107]
	s_waitcnt vmcnt(8)
	v_lshl_add_u64 v[110:111], v[194:195], 0, v[106:107]
	v_lshl_add_u64 v[116:117], v[192:193], 0, v[114:115]
	v_lshl_add_u64 v[114:115], v[194:195], 0, v[114:115]
	v_lshl_add_u64 v[200:201], v[100:101], 0, s[70:71]
	v_lshl_add_u64 v[202:203], v[108:109], 0, s[70:71]
	v_lshl_add_u64 v[204:205], v[116:117], 0, s[70:71]
	global_load_dwordx4 v[98:101], v[100:101], off
	s_nop 0
	global_load_dwordx4 v[102:105], v[102:103], off
	s_nop 0
	global_load_dwordx4 v[106:109], v[108:109], off
	s_nop 0
	global_load_dwordx4 v[110:113], v[110:111], off
	s_nop 0
	global_load_dwordx4 v[130:133], v[116:117], off
	global_load_dwordx4 v[134:137], v[114:115], off
	v_or_b32_e32 v114, s65, v155
	v_lshlrev_b32_e32 v114, s63, v114
	v_add_u32_e32 v148, s64, v114
	v_lshlrev_b64 v[114:115], 13, v[148:149]
	v_lshl_add_u64 v[116:117], v[192:193], 0, v[114:115]
	v_lshl_add_u64 v[206:207], v[116:117], 0, s[70:71]
	v_lshl_add_u64 v[114:115], v[194:195], 0, v[114:115]
	global_load_dwordx4 v[138:141], v[116:117], off
	global_load_dwordx4 v[142:145], v[114:115], off
	v_add_u32_e32 v148, v157, v167
	v_add_u32_e32 v185, v173, v175
	s_mul_i32 s38, s67, 31
	s_waitcnt vmcnt(11)
	ds_write_b128 v148, v[50:53] offset:4608
	s_waitcnt vmcnt(10)
	ds_write_b128 v148, v[54:57] offset:5760
	s_waitcnt vmcnt(9)
	ds_write_b128 v148, v[58:61] offset:6912
	s_waitcnt vmcnt(8)
	ds_write_b128 v148, v[62:65] offset:8064
	ds_read_b128 v[114:117], v185 offset:4608
	ds_read_b128 v[118:121], v185 offset:4640
	ds_read_b128 v[122:125], v185 offset:4672
	ds_read_b128 v[126:129], v185 offset:4704
	v_mov_b32_e32 v50, s66
	v_mad_u32_u24 v187, s67, v183, v50
	s_add_i32 s66, s68, s38
	v_subrev_u32_e32 v189, 32, v187
	s_add_i32 s67, s65, 32
	s_cmp_gt_i32 s67, s66
	s_cbranch_scc1 .Ldsa_pro_nopf
	global_load_dwordx4 v[66:69], v[200:201], off
	global_load_dwordx4 v[70:73], v[200:201], off offset:1536
	v_lshl_add_u64 v[200:201], v[200:201], 0, s[70:71]
	global_load_dwordx4 v[74:77], v[202:203], off
	global_load_dwordx4 v[78:81], v[202:203], off offset:1536
	v_lshl_add_u64 v[202:203], v[202:203], 0, s[70:71]
	global_load_dwordx4 v[82:85], v[204:205], off
	global_load_dwordx4 v[86:89], v[204:205], off offset:1536
	v_lshl_add_u64 v[204:205], v[204:205], 0, s[70:71]
	global_load_dwordx4 v[90:93], v[206:207], off
	global_load_dwordx4 v[94:97], v[206:207], off offset:1536
	v_lshl_add_u64 v[206:207], v[206:207], 0, s[70:71]

; #define DSA_LD(KF, VR, KK) do { _Pragma("unroll") for (int i = 0; i < 4; ++i) { const int id = lane + 64 * i; KF[i] = *(const bf16x8*)(kcol + (size_t)(cm + (((KK) + (id >> 3)) << sh)) * QKVW + (id & 7) * 8); VR[i] = *(const u32x4*)(vcol + (size_t)(cm + (((KK) + (id >> 3)) << sh)) * QKVW + (id & 7) * 8); } } while (0)
; __device__ __forceinline__ void dsa_item(bf16_t* qkv, const float* mref_tab, LAS unsigned char* vl, int hs, int c, int i0, int lane, bool dry) {
;     ...
;         bf16x8 kfA[4], kfB[4]; u32x4 vrA[4], vrB[4];
;         int k0 = ks;
;         DSA_LD(kfA, vrA, k0);
;         for (;;) {
;             const bool m1 = k0 + 32 <= qmax; if (m1) DSA_LD(kfB, vrB, k0 + 32);
;             DSA_TILE(kfA, vrA, k0);
;             if (!m1) break;
;             const bool m2 = k0 + 64 <= qmax; if (m2) DSA_LD(kfA, vrA, k0 + 64);
;             DSA_TILE(kfB, vrB, k0 + 32);
.LBB0_785:
	s_waitcnt vmcnt(15)
	ds_write_b128 v148, v[66:69] offset:4608
	s_waitcnt vmcnt(13)
	ds_write_b128 v148, v[74:77] offset:5760
	s_waitcnt vmcnt(11)
	ds_write_b128 v148, v[82:85] offset:6912
	s_waitcnt vmcnt(9)
	ds_write_b128 v148, v[90:93] offset:8064
	ds_read_b128 v[236:239], v185 offset:4608
	ds_read_b128 v[240:243], v185 offset:4640
	v_sub_u32_e32 v219, v189, v219
	v_sub_u32_e32 v220, v189, v220
	v_cmp_gt_u32_e32 vcc, s57, v219
	s_waitcnt lgkmcnt(1)
	v_mfma_f32_32x32x16_bf16 v[50:65], v[236:239], v[114:117], v[2:17]
	ds_read_b128 v[236:239], v185 offset:4672
	v_sub_u32_e32 v221, v189, v221
	v_sub_u32_e32 v222, v189, v222
	v_sub_u32_e32 v224, v189, v224
	v_sub_u32_e32 v223, v189, v223
	v_sub_u32_e32 v233, v189, v233
	v_sub_u32_e32 v234, v189, v234
	s_waitcnt lgkmcnt(1)
	v_mfma_f32_32x32x16_bf16 v[50:65], v[240:243], v[118:121], v[50:65]
	ds_read_b128 v[240:243], v185 offset:4704
	ds_write_b128 v148, v[70:73]
	ds_write_b128 v148, v[78:81] offset:1152
	ds_write_b128 v148, v[86:89] offset:2304
	s_waitcnt vmcnt(8)
	ds_write_b128 v148, v[94:97] offset:3456
	s_cmp_lg_u64 s[38:39], 0
	s_cbranch_scc0 .Ldsa_b_nomid
	s_add_i32 s67, s65, 32
	s_cmp_gt_i32 s67, s66
	s_cbranch_scc1 .Ldsa_b_nomid
	s_nop 1
	global_load_dwordx4 v[66:69], v[200:201], off
	global_load_dwordx4 v[70:73], v[200:201], off offset:1536
	v_lshl_add_u64 v[200:201], v[200:201], 0, s[70:71]
	global_load_dwordx4 v[74:77], v[202:203], off
	global_load_dwordx4 v[78:81], v[202:203], off offset:1536
	v_lshl_add_u64 v[202:203], v[202:203], 0, s[70:71]
	global_load_dwordx4 v[82:85], v[204:205], off
	global_load_dwordx4 v[86:89], v[204:205], off offset:1536
	v_lshl_add_u64 v[204:205], v[204:205], 0, s[70:71]
	global_load_dwordx4 v[90:93], v[206:207], off
	global_load_dwordx4 v[94:97], v[206:207], off offset:1536
	v_lshl_add_u64 v[206:207], v[206:207], 0, s[70:71]
.Ldsa_b_nomid:
	s_waitcnt lgkmcnt(5)
	v_mfma_f32_32x32x16_bf16 v[50:65], v[236:239], v[122:125], v[50:65]
	s_waitcnt lgkmcnt(4)
	v_mfma_f32_32x32x16_bf16 v[50:65], v[240:243], v[126:129], v[50:65]
	s_nop 11
	v_exp_f32_e32 v50, v50
	v_exp_f32_e32 v51, v51
	v_exp_f32_e32 v52, v52
	v_exp_f32_e32 v53, v53
	v_exp_f32_e32 v54, v54
	v_cndmask_b32_e32 v219, 0, v50, vcc
	v_cmp_gt_u32_e32 vcc, s57, v220
	v_exp_f32_e32 v55, v55
	v_exp_f32_e32 v56, v56
	v_cndmask_b32_e32 v220, 0, v51, vcc
	v_cmp_gt_u32_e32 vcc, s57, v221
	v_exp_f32_e32 v57, v57
	v_add_f32_e32 v50, 0, v219
	v_cndmask_b32_e32 v221, 0, v52, vcc
	v_cmp_gt_u32_e32 vcc, s57, v222
	v_exp_f32_e32 v51, v58
	v_add_f32_e32 v50, v220, v50
	v_cndmask_b32_e32 v222, 0, v53, vcc
	v_cmp_gt_u32_e32 vcc, s57, v224
	v_add_f32_e32 v50, v221, v50
	v_sub_u32_e32 v52, v189, v225
	v_cndmask_b32_e32 v224, 0, v54, vcc
	v_cmp_gt_u32_e32 vcc, s57, v223
	v_add_f32_e32 v50, v222, v50
	v_add_f32_e32 v50, v224, v50
	v_cndmask_b32_e32 v223, 0, v55, vcc
	v_cmp_gt_u32_e32 vcc, s57, v233
	v_add_f32_e32 v50, v223, v50
	v_exp_f32_e32 v63, v63
	v_cndmask_b32_e32 v233, 0, v56, vcc
	v_cmp_gt_u32_e32 vcc, s57, v234
	v_add_f32_e32 v50, v233, v50
	v_cvt_pk_bf16_f32 v54, v219, v220
	v_cndmask_b32_e32 v57, 0, v57, vcc
	v_cmp_gt_u32_e32 vcc, s57, v52
	v_sub_u32_e32 v52, v189, v226
	v_add_f32_e32 v50, v57, v50
	v_cndmask_b32_e32 v225, 0, v51, vcc
	v_exp_f32_e32 v51, v59
	v_cmp_gt_u32_e32 vcc, s57, v52
	v_add_f32_e32 v50, v225, v50
	v_exp_f32_e32 v52, v62
	v_cndmask_b32_e32 v226, 0, v51, vcc
	v_exp_f32_e32 v51, v60
	v_add_f32_e32 v234, v226, v50
	v_sub_u32_e32 v50, v189, v227
	v_cmp_gt_u32_e32 vcc, s57, v50
	v_exp_f32_e32 v50, v61
	v_cvt_pk_bf16_f32 v55, v221, v222
	v_cndmask_b32_e32 v227, 0, v51, vcc
	v_sub_u32_e32 v51, v189, v228
	v_cmp_gt_u32_e32 vcc, s57, v51
	v_cvt_pk_bf16_f32 v56, v224, v223
	v_cvt_pk_bf16_f32 v57, v233, v57
	v_cndmask_b32_e32 v62, 0, v50, vcc
	v_sub_u32_e32 v50, v189, v229
	v_cmp_gt_u32_e32 vcc, s57, v50
	v_sub_u32_e32 v229, v189, v230
	v_exp_f32_e32 v64, v64
	v_cndmask_b32_e32 v228, 0, v52, vcc
	ds_read_b64_tr_b16 v[50:51], v218
	ds_read_b64_tr_b16 v[52:53], v218 offset:1152
	ds_read_b64_tr_b16 v[60:61], v218 offset:1216
	ds_read_b64_tr_b16 v[58:59], v218 offset:64
	s_waitcnt lgkmcnt(2)
	v_mfma_f32_32x32x16_bf16 v[34:49], v[50:53], v[54:57], v[34:49]
	v_cmp_gt_u32_e32 vcc, s57, v229
	v_sub_u32_e32 v50, v189, v231
	v_exp_f32_e32 v65, v65
	v_cndmask_b32_e32 v63, 0, v63, vcc
	v_cmp_gt_u32_e32 vcc, s57, v50
	ds_read_b64_tr_b16 v[50:51], v218 offset:2304
	ds_read_b64_tr_b16 v[52:53], v218 offset:3456
	v_sub_u32_e32 v219, v189, v232
	s_waitcnt lgkmcnt(2)
	v_mfma_f32_32x32x16_bf16 v[18:33], v[58:61], v[54:57], v[18:33]
	ds_read_b64_tr_b16 v[60:61], v218 offset:3520
	ds_read_b64_tr_b16 v[58:59], v218 offset:2368
	v_cndmask_b32_e32 v64, 0, v64, vcc
	v_cmp_gt_u32_e32 vcc, s57, v219
	v_cvt_pk_bf16_f32 v54, v225, v226
	v_cvt_pk_bf16_f32 v55, v227, v62
	v_cndmask_b32_e32 v65, 0, v65, vcc
	v_cvt_pk_bf16_f32 v56, v228, v63
	v_cvt_pk_bf16_f32 v57, v64, v65
	s_waitcnt lgkmcnt(2)
	s_nop 0
	v_mfma_f32_32x32x16_bf16 v[34:49], v[50:53], v[54:57], v[34:49]
	v_add_f32_e32 v50, v227, v234
	v_add_f32_e32 v50, v62, v50
	v_add_f32_e32 v50, v228, v50
	v_add_f32_e32 v50, v63, v50
	v_add_f32_e32 v50, v64, v50
	v_add_f32_e32 v50, v65, v50
	v_add_f32_e32 v181, v181, v50
	s_waitcnt lgkmcnt(0)
	v_mfma_f32_32x32x16_bf16 v[18:33], v[58:61], v[54:57], v[18:33]
	s_xor_b64 s[38:39], s[38:39], -1
	s_andn2_b64 vcc, exec, s[38:39]
	s_cbranch_vccz .LBB0_783

; #define DSA_LD(KF, VR, KK) do { _Pragma("unroll") for (int i = 0; i < 4; ++i) { const int id = lane + 64 * i; KF[i] = *(const bf16x8*)(kcol + (size_t)(cm + (((KK) + (id >> 3)) << sh)) * QKVW + (id & 7) * 8); VR[i] = *(const u32x4*)(vcol + (size_t)(cm + (((KK) + (id >> 3)) << sh)) * QKVW + (id & 7) * 8); } } while (0)
; __device__ __forceinline__ void dsa_item(bf16_t* qkv, const float* mref_tab, LAS unsigned char* vl, int hs, int c, int i0, int lane, bool dry) {
;     ...
;         bf16x8 kfA[4], kfB[4]; u32x4 vrA[4], vrB[4];
;         int k0 = ks;
;         DSA_LD(kfA, vrA, k0);
;         for (;;) {
;             const bool m1 = k0 + 32 <= qmax; if (m1) DSA_LD(kfB, vrB, k0 + 32);
;             DSA_TILE(kfA, vrA, k0);
;             if (!m1) break;
;             const bool m2 = k0 + 64 <= qmax; if (m2) DSA_LD(kfA, vrA, k0 + 64);
;             DSA_TILE(kfB, vrB, k0 + 32);
;             if (!m2) break;
;             k0 += 64;
;         }
.LBB0_788:
	s_waitcnt vmcnt(15)
	ds_write_b128 v148, v[98:101] offset:4608
	s_waitcnt vmcnt(13)
	ds_write_b128 v148, v[106:109] offset:5760
	s_waitcnt vmcnt(11)
	ds_write_b128 v148, v[130:133] offset:6912
	s_waitcnt vmcnt(9)
	ds_write_b128 v148, v[138:141] offset:8064
	ds_read_b128 v[218:221], v185 offset:4608
	ds_read_b128 v[222:225], v185 offset:4640
	ds_read_b128 v[226:229], v185 offset:4672
	ds_read_b128 v[230:233], v185 offset:4704
	ds_write_b128 v148, v[102:105]
	ds_write_b128 v148, v[110:113] offset:1152
	ds_write_b128 v148, v[134:137] offset:2304
	s_waitcnt vmcnt(8)
	ds_write_b128 v148, v[142:145] offset:3456
	s_add_i32 s67, s65, 64
	s_cmp_gt_i32 s67, s66
	s_cbranch_scc1 .Ldsa_a_nomid
	s_nop 1
	global_load_dwordx4 v[98:101], v[200:201], off
	global_load_dwordx4 v[102:105], v[200:201], off offset:1536
	v_lshl_add_u64 v[200:201], v[200:201], 0, s[70:71]
	global_load_dwordx4 v[106:109], v[202:203], off
	global_load_dwordx4 v[110:113], v[202:203], off offset:1536
	v_lshl_add_u64 v[202:203], v[202:203], 0, s[70:71]
	global_load_dwordx4 v[130:133], v[204:205], off
	global_load_dwordx4 v[134:137], v[204:205], off offset:1536
	v_lshl_add_u64 v[204:205], v[204:205], 0, s[70:71]
	global_load_dwordx4 v[138:141], v[206:207], off
	global_load_dwordx4 v[142:145], v[206:207], off offset:1536
	v_lshl_add_u64 v[206:207], v[206:207], 0, s[70:71]
.Ldsa_a_nomid:
	s_waitcnt lgkmcnt(7)
	v_mfma_f32_32x32x16_bf16 v[50:65], v[218:221], v[114:117], v[2:17]
	v_add_u32_e32 v219, s65, v177
	v_sub_u32_e32 v218, v187, v219
	v_add_u32_e32 v220, 1, v219
	v_add_u32_e32 v221, 2, v219
	v_cmp_gt_u32_e32 vcc, s57, v218
	v_add_u32_e32 v234, 11, v219
	v_add_u32_e32 v218, v196, v197
	s_waitcnt lgkmcnt(6)
	v_mfma_f32_32x32x16_bf16 v[50:65], v[222:225], v[118:121], v[50:65]
	v_sub_u32_e32 v225, v187, v220
	v_add_u32_e32 v222, 3, v219
	v_add_u32_e32 v224, 8, v219
	v_add_u32_e32 v223, 9, v219
	s_waitcnt lgkmcnt(5)
	v_mfma_f32_32x32x16_bf16 v[50:65], v[226:229], v[122:125], v[50:65]
	v_sub_u32_e32 v226, v187, v221
	v_sub_u32_e32 v227, v187, v222
	v_sub_u32_e32 v228, v187, v224
	v_sub_u32_e32 v229, v187, v223
	s_waitcnt lgkmcnt(4)
	v_mfma_f32_32x32x16_bf16 v[50:65], v[230:233], v[126:129], v[50:65]
	v_add_u32_e32 v233, 10, v219
	v_add_u32_e32 v230, 25, v219
	s_nop 9
	v_exp_f32_e32 v50, v50
	v_exp_f32_e32 v51, v51
	v_exp_f32_e32 v52, v52
	v_exp_f32_e32 v53, v53
	v_exp_f32_e32 v54, v54
	v_cndmask_b32_e32 v231, 0, v50, vcc
	v_cmp_gt_u32_e32 vcc, s57, v225
	v_exp_f32_e32 v55, v55
	v_exp_f32_e32 v56, v56
	v_cndmask_b32_e32 v232, 0, v51, vcc
	v_cmp_gt_u32_e32 vcc, s57, v226
	v_sub_u32_e32 v51, v187, v233
	v_add_u32_e32 v225, 16, v219
	v_cndmask_b32_e32 v235, 0, v52, vcc
	v_cmp_gt_u32_e32 vcc, s57, v227
	v_sub_u32_e32 v52, v187, v234
	v_add_u32_e32 v226, 17, v219
	v_cndmask_b32_e32 v236, 0, v53, vcc
	v_cmp_gt_u32_e32 vcc, s57, v228
	v_add_f32_e32 v50, 0, v231
	v_add_u32_e32 v227, 18, v219
	v_cndmask_b32_e32 v237, 0, v54, vcc
	v_cmp_gt_u32_e32 vcc, s57, v229
	v_add_f32_e32 v50, v232, v50
	v_add_f32_e32 v50, v235, v50
	v_cndmask_b32_e32 v238, 0, v55, vcc
	v_cmp_gt_u32_e32 vcc, s57, v51
	v_exp_f32_e32 v51, v57
	v_add_f32_e32 v50, v236, v50
	v_cndmask_b32_e32 v239, 0, v56, vcc
	v_cmp_gt_u32_e32 vcc, s57, v52
	v_sub_u32_e32 v52, v187, v225
	v_add_f32_e32 v50, v237, v50
	v_cndmask_b32_e32 v57, 0, v51, vcc
	v_exp_f32_e32 v51, v58
	v_cmp_gt_u32_e32 vcc, s57, v52
	v_sub_u32_e32 v52, v187, v226
	v_add_u32_e32 v228, 19, v219
	v_cndmask_b32_e32 v240, 0, v51, vcc
	v_exp_f32_e32 v51, v59
	v_cmp_gt_u32_e32 vcc, s57, v52
	v_sub_u32_e32 v52, v187, v227
	v_add_f32_e32 v50, v238, v50
	v_cndmask_b32_e32 v241, 0, v51, vcc
	v_exp_f32_e32 v51, v60
	v_cmp_gt_u32_e32 vcc, s57, v52
	v_sub_u32_e32 v52, v187, v228
	v_add_f32_e32 v50, v239, v50
	v_cndmask_b32_e32 v242, 0, v51, vcc
	v_exp_f32_e32 v51, v61
	v_cmp_gt_u32_e32 vcc, s57, v52
	v_add_f32_e32 v50, v57, v50
	v_add_f32_e32 v50, v240, v50
	v_cndmask_b32_e32 v243, 0, v51, vcc
	v_exp_f32_e32 v51, v62
	v_add_u32_e32 v229, 24, v219
	v_add_f32_e32 v50, v241, v50
	v_sub_u32_e32 v52, v187, v229
	v_add_f32_e32 v50, v242, v50
	v_cmp_gt_u32_e32 vcc, s57, v52
	v_add_f32_e32 v50, v243, v50
	v_exp_f32_e32 v55, v63
	v_cndmask_b32_e32 v62, 0, v51, vcc
	v_add_f32_e32 v244, v62, v50
	ds_read_b64_tr_b16 v[50:51], v218
	ds_read_b64_tr_b16 v[52:53], v218 offset:1152
	ds_read_b64_tr_b16 v[60:61], v218 offset:1216
	ds_read_b64_tr_b16 v[58:59], v218 offset:64
	v_sub_u32_e32 v54, v187, v230
	v_cmp_gt_u32_e32 vcc, s57, v54
	v_cvt_pk_bf16_f32 v54, v231, v232
	v_cvt_pk_bf16_f32 v56, v237, v238
	v_cndmask_b32_e32 v63, 0, v55, vcc
	v_cvt_pk_bf16_f32 v55, v235, v236
	v_cvt_pk_bf16_f32 v57, v239, v57
	v_exp_f32_e32 v64, v64
	v_add_u32_e32 v231, 26, v219
	s_waitcnt lgkmcnt(2)
	v_mfma_f32_32x32x16_bf16 v[34:49], v[50:53], v[54:57], v[34:49]
	v_sub_u32_e32 v50, v187, v231
	v_exp_f32_e32 v65, v65
	v_cmp_gt_u32_e32 vcc, s57, v50
	v_add_u32_e32 v232, 27, v219
	ds_read_b64_tr_b16 v[50:51], v218 offset:2304
	ds_read_b64_tr_b16 v[52:53], v218 offset:3456
	v_sub_u32_e32 v235, v187, v232
	v_cndmask_b32_e32 v64, 0, v64, vcc
	s_waitcnt lgkmcnt(2)
	v_mfma_f32_32x32x16_bf16 v[18:33], v[58:61], v[54:57], v[18:33]
	ds_read_b64_tr_b16 v[60:61], v218 offset:3520
	ds_read_b64_tr_b16 v[58:59], v218 offset:2368
	v_cmp_gt_u32_e32 vcc, s57, v235
	v_cvt_pk_bf16_f32 v54, v240, v241
	v_cvt_pk_bf16_f32 v55, v242, v243
	v_cndmask_b32_e32 v65, 0, v65, vcc
	v_cvt_pk_bf16_f32 v56, v62, v63
	v_cvt_pk_bf16_f32 v57, v64, v65
	s_andn2_b64 vcc, exec, s[38:39]
	s_waitcnt lgkmcnt(2)
	v_mfma_f32_32x32x16_bf16 v[34:49], v[50:53], v[54:57], v[34:49]
	v_add_f32_e32 v50, v63, v244
	v_add_f32_e32 v50, v64, v50
	v_add_f32_e32 v50, v65, v50
	v_add_f32_e32 v181, v181, v50
	s_waitcnt lgkmcnt(0)
	v_mfma_f32_32x32x16_bf16 v[18:33], v[58:61], v[54:57], v[18:33]
	s_cbranch_vccnz .LBB0_791
	s_add_i32 s67, s65, 64
	s_cmp_le_i32 s67, s66
	s_cselect_b64 s[38:39], -1, 0
	s_cmp_gt_i32 s67, s66
	s_cbranch_scc1 .Ldsa_b_nopf
	s_mov_b32 s65, s67
	s_branch .LBB0_785
